# attnA: second softmax group's exps and row-sum adds also issued inside the QK MFMA shadows
# speedup vs baseline: 1.0050x; 1.0050x over previous
.LBB0_1369:
	s_or_b32 s82, s34, 1
	s_lshl_b64 s[4:5], s[82:83], 7
	s_add_u32 s4, s8, s4
	s_addc_u32 s5, s9, s5
	s_add_u32 m0, s38, 0x8000
	s_nop 0
	global_load_lds_dwordx4 v198, s[4:5]
	s_add_u32 m0, s38, 0x9000
	s_nop 0
	global_load_lds_dwordx4 v199, s[4:5]
	s_add_u32 m0, s38, 0xa000
	s_nop 0
	global_load_lds_dwordx4 v200, s[4:5]
	s_add_u32 m0, s38, 0xb000
	s_nop 0
	global_load_lds_dwordx4 v201, s[4:5]
	v_cmp_lt_i32_e64 s[4:5], s34, v226
	s_and_saveexec_b64 s[22:23], s[4:5]
	s_cbranch_execz .LBB0_1371
	ds_read_b128 v[2:5], v222 offset:24576
	ds_read_b128 v[6:9], v222 offset:28672
	ds_read_b128 v[10:13], v223 offset:24576
	ds_read_b128 v[244:247], v223 offset:28672
	s_waitcnt lgkmcnt(3)
	v_mfma_f32_32x32x16_bf16 v[128:143], v[2:5], v[160:163], v[16:31]
	v_exp_f32_e32 v32, v32
	v_exp_f32_e32 v33, v33
	v_exp_f32_e32 v34, v34
	ds_read_b128 v[2:5], v224 offset:24576
	s_waitcnt lgkmcnt(3)
	v_mfma_f32_32x32x16_bf16 v[144:159], v[6:9], v[160:163], v[16:31]
	v_exp_f32_e32 v35, v35
	v_exp_f32_e32 v36, v36
	v_exp_f32_e32 v37, v37
	ds_read_b128 v[6:9], v224 offset:28672
	s_waitcnt lgkmcnt(3)
	v_mfma_f32_32x32x16_bf16 v[128:143], v[10:13], v[164:167], v[128:143]
	v_exp_f32_e32 v38, v38
	v_exp_f32_e32 v39, v39
	v_add_f32_e32 v0, 0, v32
	v_add_f32_e32 v0, v33, v0
	ds_read_b128 v[10:13], v225 offset:24576
	s_waitcnt lgkmcnt(3)
	v_mfma_f32_32x32x16_bf16 v[144:159], v[244:247], v[164:167], v[144:159]
	v_exp_f32_e32 v40, v40
	v_exp_f32_e32 v41, v41
	v_add_f32_e32 v0, v34, v0
	v_add_f32_e32 v0, v35, v0
	v_cvt_pk_bf16_f32 v208, v32, v33
	ds_read_b128 v[244:247], v225 offset:28672
	s_waitcnt lgkmcnt(3)
	v_mfma_f32_32x32x16_bf16 v[128:143], v[2:5], v[168:171], v[128:143]
	v_exp_f32_e32 v42, v42
	v_exp_f32_e32 v43, v43
	v_add_f32_e32 v0, v36, v0
	v_add_f32_e32 v0, v37, v0
	v_cvt_pk_bf16_f32 v209, v34, v35
	s_waitcnt lgkmcnt(2)
	v_mfma_f32_32x32x16_bf16 v[144:159], v[6:9], v[168:171], v[144:159]
	v_exp_f32_e32 v44, v44
	v_exp_f32_e32 v45, v45
	v_add_f32_e32 v0, v38, v0
	v_add_f32_e32 v0, v39, v0
	v_cvt_pk_bf16_f32 v210, v36, v37
	v_cvt_pk_bf16_f32 v211, v38, v39
	s_waitcnt lgkmcnt(1)
	v_mfma_f32_32x32x16_bf16 v[128:143], v[10:13], v[172:175], v[128:143]
	v_exp_f32_e32 v46, v46
	v_exp_f32_e32 v47, v47
	v_add_f32_e32 v0, v40, v0
	v_add_f32_e32 v0, v41, v0
	v_add_f32_e32 v0, v42, v0
	s_waitcnt lgkmcnt(0)
	v_mfma_f32_32x32x16_bf16 v[144:159], v[244:247], v[172:175], v[144:159]
	v_add_f32_e32 v0, v43, v0
	v_add_f32_e32 v0, v44, v0
	v_add_f32_e32 v0, v45, v0
	v_add_f32_e32 v0, v46, v0
	v_add_f32_e32 v0, v47, v0
	s_or_b64 exec, exec, s[22:23]
	v_cmp_le_i32_e32 vcc, s34, v226
	s_and_saveexec_b64 s[22:23], vcc
	ds_read_b64 v[6:7], v228 offset:8192
	ds_read_b64 v[8:9], v229 offset:8192
	ds_read_b64 v[10:11], v230 offset:20480
	ds_read_b64 v[12:13], v231 offset:20480
	ds_read_b64 v[244:245], v230 offset:12288
	ds_read_b64 v[246:247], v231 offset:12288
	ds_read_b64 v[32:33], v230 offset:16384
	ds_read_b64 v[34:35], v231 offset:16384
	ds_read_b64 v[36:37], v232 offset:8192
	ds_read_b64 v[38:39], v233 offset:8192
	s_waitcnt lgkmcnt(8)
	v_mfma_f32_32x32x16_bf16 v[112:127], v[6:9], v[208:211], v[112:127]
	ds_read_b64 v[6:7], v234 offset:20480
	ds_read_b64 v[8:9], v235 offset:20480
	s_waitcnt lgkmcnt(8)
	v_mfma_f32_32x32x16_bf16 v[64:79], v[10:13], v[208:211], v[64:79]
	ds_read_b64 v[10:11], v234 offset:12288
	ds_read_b64 v[12:13], v235 offset:12288
	s_waitcnt lgkmcnt(8)
	v_mfma_f32_32x32x16_bf16 v[96:111], v[244:247], v[208:211], v[96:111]
	ds_read_b64 v[244:245], v234 offset:16384
	ds_read_b64 v[246:247], v235 offset:16384
	s_waitcnt lgkmcnt(8)
	v_mfma_f32_32x32x16_bf16 v[80:95], v[32:35], v[208:211], v[80:95]
	ds_read_b64 v[32:33], v236 offset:8192
	ds_read_b64 v[34:35], v237 offset:8192
	v_cvt_pk_bf16_f32 v2, v40, v41
	v_cvt_pk_bf16_f32 v3, v42, v43
	v_cvt_pk_bf16_f32 v4, v44, v45
	v_cvt_pk_bf16_f32 v5, v46, v47
	s_nop 1
	ds_read_b64 v[40:41], v238 offset:20480
	ds_read_b64 v[42:43], v239 offset:20480
	s_waitcnt lgkmcnt(10)
	v_mfma_f32_32x32x16_bf16 v[112:127], v[36:39], v[2:5], v[112:127]
	ds_read_b64 v[44:45], v238 offset:12288
	ds_read_b64 v[46:47], v239 offset:12288
	v_exp_f32_e32 v48, v48
	v_exp_f32_e32 v49, v49
	s_waitcnt lgkmcnt(10)
	v_mfma_f32_32x32x16_bf16 v[64:79], v[6:9], v[2:5], v[64:79]
	ds_read_b64 v[36:37], v238 offset:16384
	ds_read_b64 v[38:39], v239 offset:16384
	v_exp_f32_e32 v50, v50
	v_exp_f32_e32 v51, v51
	v_add_f32_e32 v0, v48, v0
	v_add_f32_e32 v0, v49, v0
	s_waitcnt lgkmcnt(10)
	v_mfma_f32_32x32x16_bf16 v[96:111], v[10:13], v[2:5], v[96:111]
	ds_read_b64 v[6:7], v240 offset:8192
	ds_read_b64 v[8:9], v241 offset:8192
	v_exp_f32_e32 v52, v52
	v_exp_f32_e32 v53, v53
	v_add_f32_e32 v0, v50, v0
	v_add_f32_e32 v0, v51, v0
	s_waitcnt lgkmcnt(10)
	v_mfma_f32_32x32x16_bf16 v[80:95], v[244:247], v[2:5], v[80:95]
	ds_read_b64 v[10:11], v242 offset:12288
	ds_read_b64 v[12:13], v243 offset:12288
	v_exp_f32_e32 v54, v54
	v_exp_f32_e32 v55, v55
	v_add_f32_e32 v0, v52, v0
	v_add_f32_e32 v0, v53, v0
	v_add_f32_e32 v0, v54, v0
	v_add_f32_e32 v0, v55, v0
	v_cvt_pk_bf16_f32 v2, v48, v49
	v_cvt_pk_bf16_f32 v3, v50, v51
	v_cvt_pk_bf16_f32 v4, v52, v53
	v_cvt_pk_bf16_f32 v5, v54, v55
	s_nop 1
	ds_read_b64 v[244:245], v242 offset:16384
	ds_read_b64 v[246:247], v243 offset:16384
	s_waitcnt lgkmcnt(12)
	v_mfma_f32_32x32x16_bf16 v[112:127], v[32:35], v[2:5], v[112:127]
	ds_read_b64 v[48:49], v242 offset:20480
	ds_read_b64 v[50:51], v243 offset:20480
	v_exp_f32_e32 v56, v56
	v_exp_f32_e32 v57, v57
	s_waitcnt lgkmcnt(12)
	v_mfma_f32_32x32x16_bf16 v[64:79], v[40:43], v[2:5], v[64:79]
	v_exp_f32_e32 v58, v58
	v_exp_f32_e32 v59, v59
	v_add_f32_e32 v0, v56, v0
	v_add_f32_e32 v0, v57, v0
	s_waitcnt lgkmcnt(10)
	v_mfma_f32_32x32x16_bf16 v[96:111], v[44:47], v[2:5], v[96:111]
	v_exp_f32_e32 v60, v60
	v_exp_f32_e32 v61, v61
	v_add_f32_e32 v0, v58, v0
	v_add_f32_e32 v0, v59, v0
	s_waitcnt lgkmcnt(8)
	v_mfma_f32_32x32x16_bf16 v[80:95], v[36:39], v[2:5], v[80:95]
	v_exp_f32_e32 v62, v62
	v_exp_f32_e32 v63, v63
	v_add_f32_e32 v0, v60, v0
	v_add_f32_e32 v0, v61, v0
	v_add_f32_e32 v0, v62, v0
	v_add_f32_e32 v0, v63, v0
	v_cvt_pk_bf16_f32 v2, v56, v57
	v_cvt_pk_bf16_f32 v3, v58, v59
	v_cvt_pk_bf16_f32 v4, v60, v61
	v_cvt_pk_bf16_f32 v5, v62, v63
	s_nop 1
	s_waitcnt lgkmcnt(6)
	v_mfma_f32_32x32x16_bf16 v[112:127], v[6:9], v[2:5], v[112:127]
	s_waitcnt lgkmcnt(4)
	v_mfma_f32_32x32x16_bf16 v[96:111], v[10:13], v[2:5], v[96:111]
	s_waitcnt lgkmcnt(2)
	v_mfma_f32_32x32x16_bf16 v[80:95], v[244:247], v[2:5], v[80:95]
	s_waitcnt lgkmcnt(0)
	v_mfma_f32_32x32x16_bf16 v[64:79], v[48:51], v[2:5], v[64:79]
	v_add_f32_e32 v227, v227, v0
	s_branch .LBB0_1373

.LBB0_1381:
	ds_read_b128 v[2:5], v222
	ds_read_b128 v[6:9], v222 offset:4096
	ds_read_b128 v[10:13], v223
	ds_read_b128 v[244:247], v223 offset:4096
	s_waitcnt lgkmcnt(3)
	v_mfma_f32_32x32x16_bf16 v[32:47], v[2:5], v[160:163], v[16:31]
	v_exp_f32_e32 v128, v128
	v_exp_f32_e32 v129, v129
	v_exp_f32_e32 v130, v130
	ds_read_b128 v[2:5], v224
	s_waitcnt lgkmcnt(3)
	v_mfma_f32_32x32x16_bf16 v[48:63], v[6:9], v[160:163], v[16:31]
	v_exp_f32_e32 v131, v131
	v_exp_f32_e32 v132, v132
	v_exp_f32_e32 v133, v133
	ds_read_b128 v[6:9], v224 offset:4096
	s_waitcnt lgkmcnt(3)
	v_mfma_f32_32x32x16_bf16 v[32:47], v[10:13], v[164:167], v[32:47]
	v_exp_f32_e32 v134, v134
	v_exp_f32_e32 v135, v135
	v_add_f32_e32 v0, 0, v128
	v_add_f32_e32 v0, v129, v0
	ds_read_b128 v[10:13], v225
	s_waitcnt lgkmcnt(3)
	v_mfma_f32_32x32x16_bf16 v[48:63], v[244:247], v[164:167], v[48:63]
	v_exp_f32_e32 v136, v136
	v_exp_f32_e32 v137, v137
	v_add_f32_e32 v0, v130, v0
	v_add_f32_e32 v0, v131, v0
	v_cvt_pk_bf16_f32 v208, v128, v129
	ds_read_b128 v[244:247], v225 offset:4096
	s_waitcnt lgkmcnt(3)
	v_mfma_f32_32x32x16_bf16 v[32:47], v[2:5], v[168:171], v[32:47]
	v_exp_f32_e32 v138, v138
	v_exp_f32_e32 v139, v139
	v_add_f32_e32 v0, v132, v0
	v_add_f32_e32 v0, v133, v0
	v_cvt_pk_bf16_f32 v209, v130, v131
	s_waitcnt lgkmcnt(2)
	v_mfma_f32_32x32x16_bf16 v[48:63], v[6:9], v[168:171], v[48:63]
	v_exp_f32_e32 v140, v140
	v_exp_f32_e32 v141, v141
	v_add_f32_e32 v0, v134, v0
	v_add_f32_e32 v0, v135, v0
	v_cvt_pk_bf16_f32 v210, v132, v133
	v_cvt_pk_bf16_f32 v211, v134, v135
	s_waitcnt lgkmcnt(1)
	v_mfma_f32_32x32x16_bf16 v[32:47], v[10:13], v[172:175], v[32:47]
	v_exp_f32_e32 v142, v142
	v_exp_f32_e32 v143, v143
	v_add_f32_e32 v0, v136, v0
	v_add_f32_e32 v0, v137, v0
	v_add_f32_e32 v0, v138, v0
	s_waitcnt lgkmcnt(0)
	v_mfma_f32_32x32x16_bf16 v[48:63], v[244:247], v[172:175], v[48:63]
	v_add_f32_e32 v0, v139, v0
	v_add_f32_e32 v0, v140, v0
	v_add_f32_e32 v0, v141, v0
	v_add_f32_e32 v0, v142, v0
	v_add_f32_e32 v0, v143, v0
	s_or_b64 exec, exec, s[20:21]
	s_and_saveexec_b64 s[20:21], s[4:5]
	ds_read_b64 v[6:7], v228 offset:32768
	ds_read_b64 v[8:9], v229 offset:32768
	ds_read_b64 v[10:11], v230 offset:45056
	ds_read_b64 v[12:13], v231 offset:45056
	ds_read_b64 v[244:245], v230 offset:36864
	ds_read_b64 v[246:247], v231 offset:36864
	ds_read_b64 v[128:129], v230 offset:40960
	ds_read_b64 v[130:131], v231 offset:40960
	ds_read_b64 v[132:133], v232 offset:32768
	ds_read_b64 v[134:135], v233 offset:32768
	s_waitcnt lgkmcnt(8)
	v_mfma_f32_32x32x16_bf16 v[112:127], v[6:9], v[208:211], v[112:127]
	ds_read_b64 v[6:7], v234 offset:45056
	ds_read_b64 v[8:9], v235 offset:45056
	s_waitcnt lgkmcnt(8)
	v_mfma_f32_32x32x16_bf16 v[64:79], v[10:13], v[208:211], v[64:79]
	ds_read_b64 v[10:11], v234 offset:36864
	ds_read_b64 v[12:13], v235 offset:36864
	s_waitcnt lgkmcnt(8)
	v_mfma_f32_32x32x16_bf16 v[96:111], v[244:247], v[208:211], v[96:111]
	ds_read_b64 v[244:245], v234 offset:40960
	ds_read_b64 v[246:247], v235 offset:40960
	s_waitcnt lgkmcnt(8)
	v_mfma_f32_32x32x16_bf16 v[80:95], v[128:131], v[208:211], v[80:95]
	ds_read_b64 v[128:129], v236 offset:32768
	ds_read_b64 v[130:131], v237 offset:32768
	v_cvt_pk_bf16_f32 v2, v136, v137
	v_cvt_pk_bf16_f32 v3, v138, v139
	v_cvt_pk_bf16_f32 v4, v140, v141
	v_cvt_pk_bf16_f32 v5, v142, v143
	s_nop 1
	ds_read_b64 v[136:137], v238 offset:45056
	ds_read_b64 v[138:139], v239 offset:45056
	s_waitcnt lgkmcnt(10)
	v_mfma_f32_32x32x16_bf16 v[112:127], v[132:135], v[2:5], v[112:127]
	ds_read_b64 v[140:141], v238 offset:36864
	ds_read_b64 v[142:143], v239 offset:36864
	v_exp_f32_e32 v144, v144
	v_exp_f32_e32 v145, v145
	s_waitcnt lgkmcnt(10)
	v_mfma_f32_32x32x16_bf16 v[64:79], v[6:9], v[2:5], v[64:79]
	ds_read_b64 v[132:133], v238 offset:40960
	ds_read_b64 v[134:135], v239 offset:40960
	v_exp_f32_e32 v146, v146
	v_exp_f32_e32 v147, v147
	v_add_f32_e32 v0, v144, v0
	v_add_f32_e32 v0, v145, v0
	s_waitcnt lgkmcnt(10)
	v_mfma_f32_32x32x16_bf16 v[96:111], v[10:13], v[2:5], v[96:111]
	ds_read_b64 v[6:7], v240 offset:32768
	ds_read_b64 v[8:9], v241 offset:32768
	v_exp_f32_e32 v148, v148
	v_exp_f32_e32 v149, v149
	v_add_f32_e32 v0, v146, v0
	v_add_f32_e32 v0, v147, v0
	s_waitcnt lgkmcnt(10)
	v_mfma_f32_32x32x16_bf16 v[80:95], v[244:247], v[2:5], v[80:95]
	ds_read_b64 v[10:11], v242 offset:36864
	ds_read_b64 v[12:13], v243 offset:36864
	v_exp_f32_e32 v150, v150
	v_exp_f32_e32 v151, v151
	v_add_f32_e32 v0, v148, v0
	v_add_f32_e32 v0, v149, v0
	v_add_f32_e32 v0, v150, v0
	v_add_f32_e32 v0, v151, v0
	v_cvt_pk_bf16_f32 v2, v144, v145
	v_cvt_pk_bf16_f32 v3, v146, v147
	v_cvt_pk_bf16_f32 v4, v148, v149
	v_cvt_pk_bf16_f32 v5, v150, v151
	s_nop 1
	ds_read_b64 v[244:245], v242 offset:40960
	ds_read_b64 v[246:247], v243 offset:40960
	s_waitcnt lgkmcnt(12)
	v_mfma_f32_32x32x16_bf16 v[112:127], v[128:131], v[2:5], v[112:127]
	ds_read_b64 v[144:145], v242 offset:45056
	ds_read_b64 v[146:147], v243 offset:45056
	v_exp_f32_e32 v152, v152
	v_exp_f32_e32 v153, v153
	s_waitcnt lgkmcnt(12)
	v_mfma_f32_32x32x16_bf16 v[64:79], v[136:139], v[2:5], v[64:79]
	v_exp_f32_e32 v154, v154
	v_exp_f32_e32 v155, v155
	v_add_f32_e32 v0, v152, v0
	v_add_f32_e32 v0, v153, v0
	s_waitcnt lgkmcnt(10)
	v_mfma_f32_32x32x16_bf16 v[96:111], v[140:143], v[2:5], v[96:111]
	v_exp_f32_e32 v156, v156
	v_exp_f32_e32 v157, v157
	v_add_f32_e32 v0, v154, v0
	v_add_f32_e32 v0, v155, v0
	s_waitcnt lgkmcnt(8)
	v_mfma_f32_32x32x16_bf16 v[80:95], v[132:135], v[2:5], v[80:95]
	v_exp_f32_e32 v158, v158
	v_exp_f32_e32 v159, v159
	v_add_f32_e32 v0, v156, v0
	v_add_f32_e32 v0, v157, v0
	v_add_f32_e32 v0, v158, v0
	v_add_f32_e32 v0, v159, v0
	v_cvt_pk_bf16_f32 v2, v152, v153
	v_cvt_pk_bf16_f32 v3, v154, v155
	v_cvt_pk_bf16_f32 v4, v156, v157
	v_cvt_pk_bf16_f32 v5, v158, v159
	s_nop 1
	s_waitcnt lgkmcnt(6)
	v_mfma_f32_32x32x16_bf16 v[112:127], v[6:9], v[2:5], v[112:127]
	s_waitcnt lgkmcnt(4)
	v_mfma_f32_32x32x16_bf16 v[96:111], v[10:13], v[2:5], v[96:111]
	s_waitcnt lgkmcnt(2)
	v_mfma_f32_32x32x16_bf16 v[80:95], v[244:247], v[2:5], v[80:95]
	s_waitcnt lgkmcnt(0)
	v_mfma_f32_32x32x16_bf16 v[64:79], v[144:147], v[2:5], v[64:79]
	v_add_f32_e32 v227, v0, v227
	s_branch .LBB0_1386

.LBB0_1411:
	s_or_b32 s82, s31, 1
	s_lshl_b64 s[4:5], s[82:83], 7
	s_add_u32 s4, s8, s4
	s_addc_u32 s5, s9, s5
	s_add_u32 m0, s38, 0x8000
	s_nop 0
	global_load_lds_dwordx4 v196, s[4:5]
	s_add_u32 m0, s38, 0x9000
	s_nop 0
	global_load_lds_dwordx4 v197, s[4:5]
	s_add_u32 m0, s38, 0xa000
	s_nop 0
	global_load_lds_dwordx4 v198, s[4:5]
	s_add_u32 m0, s38, 0xb000
	s_nop 0
	global_load_lds_dwordx4 v199, s[4:5]
	v_cmp_lt_i32_e64 s[4:5], s31, v225
	s_and_saveexec_b64 s[22:23], s[4:5]
	s_cbranch_execz .LBB0_1413
	ds_read_b128 v[2:5], v220 offset:24576
	ds_read_b128 v[6:9], v220 offset:28672
	ds_read_b128 v[10:13], v221 offset:24576
	ds_read_b128 v[244:247], v221 offset:28672
	s_waitcnt lgkmcnt(3)
	v_mfma_f32_32x32x16_bf16 v[128:143], v[2:5], v[160:163], v[16:31]
	v_exp_f32_e32 v80, v80
	v_exp_f32_e32 v81, v81
	v_exp_f32_e32 v82, v82
	ds_read_b128 v[2:5], v222 offset:24576
	s_waitcnt lgkmcnt(3)
	v_mfma_f32_32x32x16_bf16 v[144:159], v[6:9], v[160:163], v[16:31]
	v_exp_f32_e32 v83, v83
	v_exp_f32_e32 v84, v84
	v_exp_f32_e32 v85, v85
	ds_read_b128 v[6:9], v222 offset:28672
	s_waitcnt lgkmcnt(3)
	v_mfma_f32_32x32x16_bf16 v[128:143], v[10:13], v[164:167], v[128:143]
	v_exp_f32_e32 v86, v86
	v_exp_f32_e32 v87, v87
	v_add_f32_e32 v0, 0, v80
	v_add_f32_e32 v0, v81, v0
	ds_read_b128 v[10:13], v223 offset:24576
	s_waitcnt lgkmcnt(3)
	v_mfma_f32_32x32x16_bf16 v[144:159], v[244:247], v[164:167], v[144:159]
	v_exp_f32_e32 v88, v88
	v_exp_f32_e32 v89, v89
	v_add_f32_e32 v0, v82, v0
	v_add_f32_e32 v0, v83, v0
	v_cvt_pk_bf16_f32 v208, v80, v81
	ds_read_b128 v[244:247], v223 offset:28672
	s_waitcnt lgkmcnt(3)
	v_mfma_f32_32x32x16_bf16 v[128:143], v[2:5], v[168:171], v[128:143]
	v_exp_f32_e32 v90, v90
	v_exp_f32_e32 v91, v91
	v_add_f32_e32 v0, v84, v0
	v_add_f32_e32 v0, v85, v0
	v_cvt_pk_bf16_f32 v209, v82, v83
	s_waitcnt lgkmcnt(2)
	v_mfma_f32_32x32x16_bf16 v[144:159], v[6:9], v[168:171], v[144:159]
	v_exp_f32_e32 v92, v92
	v_exp_f32_e32 v93, v93
	v_add_f32_e32 v0, v86, v0
	v_add_f32_e32 v0, v87, v0
	v_cvt_pk_bf16_f32 v210, v84, v85
	v_cvt_pk_bf16_f32 v211, v86, v87
	s_waitcnt lgkmcnt(1)
	v_mfma_f32_32x32x16_bf16 v[128:143], v[10:13], v[172:175], v[128:143]
	v_exp_f32_e32 v94, v94
	v_exp_f32_e32 v95, v95
	v_add_f32_e32 v0, v88, v0
	v_add_f32_e32 v0, v89, v0
	v_add_f32_e32 v0, v90, v0
	s_waitcnt lgkmcnt(0)
	v_mfma_f32_32x32x16_bf16 v[144:159], v[244:247], v[172:175], v[144:159]
	v_add_f32_e32 v0, v91, v0
	v_add_f32_e32 v0, v92, v0
	v_add_f32_e32 v0, v93, v0
	v_add_f32_e32 v0, v94, v0
	v_add_f32_e32 v0, v95, v0
	s_or_b64 exec, exec, s[22:23]
	v_cmp_le_i32_e32 vcc, s31, v225
	s_and_saveexec_b64 s[22:23], vcc
	ds_read_b64 v[6:7], v226 offset:8192
	ds_read_b64 v[8:9], v227 offset:8192
	ds_read_b64 v[10:11], v228 offset:20480
	ds_read_b64 v[12:13], v229 offset:20480
	ds_read_b64 v[242:243], v228 offset:12288
	ds_read_b64 v[244:245], v229 offset:12288
	ds_read_b64 v[80:81], v228 offset:16384
	ds_read_b64 v[82:83], v229 offset:16384
	ds_read_b64 v[84:85], v230 offset:8192
	ds_read_b64 v[86:87], v231 offset:8192
	s_waitcnt lgkmcnt(8)
	v_mfma_f32_32x32x16_bf16 v[64:79], v[6:9], v[208:211], v[64:79]
	ds_read_b64 v[6:7], v232 offset:20480
	ds_read_b64 v[8:9], v233 offset:20480
	s_waitcnt lgkmcnt(8)
	v_mfma_f32_32x32x16_bf16 v[112:127], v[10:13], v[208:211], v[112:127]
	ds_read_b64 v[10:11], v232 offset:12288
	ds_read_b64 v[12:13], v233 offset:12288
	s_waitcnt lgkmcnt(8)
	v_mfma_f32_32x32x16_bf16 v[48:63], v[242:245], v[208:211], v[48:63]
	ds_read_b64 v[242:243], v232 offset:16384
	ds_read_b64 v[244:245], v233 offset:16384
	s_waitcnt lgkmcnt(8)
	v_mfma_f32_32x32x16_bf16 v[32:47], v[80:83], v[208:211], v[32:47]
	ds_read_b64 v[80:81], v234 offset:8192
	ds_read_b64 v[82:83], v235 offset:8192
	v_cvt_pk_bf16_f32 v2, v88, v89
	v_cvt_pk_bf16_f32 v3, v90, v91
	v_cvt_pk_bf16_f32 v4, v92, v93
	v_cvt_pk_bf16_f32 v5, v94, v95
	s_nop 1
	ds_read_b64 v[88:89], v236 offset:20480
	ds_read_b64 v[90:91], v237 offset:20480
	s_waitcnt lgkmcnt(10)
	v_mfma_f32_32x32x16_bf16 v[64:79], v[84:87], v[2:5], v[64:79]
	ds_read_b64 v[92:93], v236 offset:12288
	ds_read_b64 v[94:95], v237 offset:12288
	v_exp_f32_e32 v96, v96
	v_exp_f32_e32 v97, v97
	s_waitcnt lgkmcnt(10)
	v_mfma_f32_32x32x16_bf16 v[112:127], v[6:9], v[2:5], v[112:127]
	ds_read_b64 v[84:85], v236 offset:16384
	ds_read_b64 v[86:87], v237 offset:16384
	v_exp_f32_e32 v98, v98
	v_exp_f32_e32 v99, v99
	v_add_f32_e32 v0, v96, v0
	v_add_f32_e32 v0, v97, v0
	s_waitcnt lgkmcnt(10)
	v_mfma_f32_32x32x16_bf16 v[48:63], v[10:13], v[2:5], v[48:63]
	ds_read_b64 v[6:7], v238 offset:8192
	ds_read_b64 v[8:9], v239 offset:8192
	v_exp_f32_e32 v100, v100
	v_exp_f32_e32 v101, v101
	v_add_f32_e32 v0, v98, v0
	v_add_f32_e32 v0, v99, v0
	s_waitcnt lgkmcnt(10)
	v_mfma_f32_32x32x16_bf16 v[32:47], v[242:245], v[2:5], v[32:47]
	ds_read_b64 v[10:11], v240 offset:12288
	ds_read_b64 v[12:13], v241 offset:12288
	v_exp_f32_e32 v102, v102
	v_exp_f32_e32 v103, v103
	v_add_f32_e32 v0, v100, v0
	v_add_f32_e32 v0, v101, v0
	v_add_f32_e32 v0, v102, v0
	v_add_f32_e32 v0, v103, v0
	v_cvt_pk_bf16_f32 v2, v96, v97
	v_cvt_pk_bf16_f32 v3, v98, v99
	v_cvt_pk_bf16_f32 v4, v100, v101
	v_cvt_pk_bf16_f32 v5, v102, v103
	s_nop 1
	ds_read_b64 v[242:243], v240 offset:16384
	ds_read_b64 v[244:245], v241 offset:16384
	s_waitcnt lgkmcnt(12)
	v_mfma_f32_32x32x16_bf16 v[64:79], v[80:83], v[2:5], v[64:79]
	ds_read_b64 v[96:97], v240 offset:20480
	ds_read_b64 v[98:99], v241 offset:20480
	v_exp_f32_e32 v104, v104
	v_exp_f32_e32 v105, v105
	s_waitcnt lgkmcnt(12)
	v_mfma_f32_32x32x16_bf16 v[112:127], v[88:91], v[2:5], v[112:127]
	v_exp_f32_e32 v106, v106
	v_exp_f32_e32 v107, v107
	v_add_f32_e32 v0, v104, v0
	v_add_f32_e32 v0, v105, v0
	s_waitcnt lgkmcnt(10)
	v_mfma_f32_32x32x16_bf16 v[48:63], v[92:95], v[2:5], v[48:63]
	v_exp_f32_e32 v108, v108
	v_exp_f32_e32 v109, v109
	v_add_f32_e32 v0, v106, v0
	v_add_f32_e32 v0, v107, v0
	s_waitcnt lgkmcnt(8)
	v_mfma_f32_32x32x16_bf16 v[32:47], v[84:87], v[2:5], v[32:47]
	v_exp_f32_e32 v110, v110
	v_exp_f32_e32 v111, v111
	v_add_f32_e32 v0, v108, v0
	v_add_f32_e32 v0, v109, v0
	v_add_f32_e32 v0, v110, v0
	v_add_f32_e32 v0, v111, v0
	v_cvt_pk_bf16_f32 v2, v104, v105
	v_cvt_pk_bf16_f32 v3, v106, v107
	v_cvt_pk_bf16_f32 v4, v108, v109
	v_cvt_pk_bf16_f32 v5, v110, v111
	s_nop 1
	s_waitcnt lgkmcnt(6)
	v_mfma_f32_32x32x16_bf16 v[64:79], v[6:9], v[2:5], v[64:79]
	s_waitcnt lgkmcnt(4)
	v_mfma_f32_32x32x16_bf16 v[48:63], v[10:13], v[2:5], v[48:63]
	s_waitcnt lgkmcnt(2)
	v_mfma_f32_32x32x16_bf16 v[32:47], v[242:245], v[2:5], v[32:47]
	s_waitcnt lgkmcnt(0)
	v_mfma_f32_32x32x16_bf16 v[112:127], v[96:99], v[2:5], v[112:127]
	v_add_f32_e32 v224, v224, v0
	s_branch .LBB0_1415

.LBB0_1423:
	ds_read_b128 v[2:5], v220
	ds_read_b128 v[6:9], v220 offset:4096
	ds_read_b128 v[10:13], v221
	ds_read_b128 v[244:247], v221 offset:4096
	s_waitcnt lgkmcnt(3)
	v_mfma_f32_32x32x16_bf16 v[80:95], v[2:5], v[160:163], v[16:31]
	v_exp_f32_e32 v128, v128
	v_exp_f32_e32 v129, v129
	v_exp_f32_e32 v130, v130
	ds_read_b128 v[2:5], v222
	s_waitcnt lgkmcnt(3)
	v_mfma_f32_32x32x16_bf16 v[96:111], v[6:9], v[160:163], v[16:31]
	v_exp_f32_e32 v131, v131
	v_exp_f32_e32 v132, v132
	v_exp_f32_e32 v133, v133
	ds_read_b128 v[6:9], v222 offset:4096
	s_waitcnt lgkmcnt(3)
	v_mfma_f32_32x32x16_bf16 v[80:95], v[10:13], v[164:167], v[80:95]
	v_exp_f32_e32 v134, v134
	v_exp_f32_e32 v135, v135
	v_add_f32_e32 v0, 0, v128
	v_add_f32_e32 v0, v129, v0
	ds_read_b128 v[10:13], v223
	s_waitcnt lgkmcnt(3)
	v_mfma_f32_32x32x16_bf16 v[96:111], v[244:247], v[164:167], v[96:111]
	v_exp_f32_e32 v136, v136
	v_exp_f32_e32 v137, v137
	v_add_f32_e32 v0, v130, v0
	v_add_f32_e32 v0, v131, v0
	v_cvt_pk_bf16_f32 v208, v128, v129
	ds_read_b128 v[244:247], v223 offset:4096
	s_waitcnt lgkmcnt(3)
	v_mfma_f32_32x32x16_bf16 v[80:95], v[2:5], v[168:171], v[80:95]
	v_exp_f32_e32 v138, v138
	v_exp_f32_e32 v139, v139
	v_add_f32_e32 v0, v132, v0
	v_add_f32_e32 v0, v133, v0
	v_cvt_pk_bf16_f32 v209, v130, v131
	s_waitcnt lgkmcnt(2)
	v_mfma_f32_32x32x16_bf16 v[96:111], v[6:9], v[168:171], v[96:111]
	v_exp_f32_e32 v140, v140
	v_exp_f32_e32 v141, v141
	v_add_f32_e32 v0, v134, v0
	v_add_f32_e32 v0, v135, v0
	v_cvt_pk_bf16_f32 v210, v132, v133
	v_cvt_pk_bf16_f32 v211, v134, v135
	s_waitcnt lgkmcnt(1)
	v_mfma_f32_32x32x16_bf16 v[80:95], v[10:13], v[172:175], v[80:95]
	v_exp_f32_e32 v142, v142
	v_exp_f32_e32 v143, v143
	v_add_f32_e32 v0, v136, v0
	v_add_f32_e32 v0, v137, v0
	v_add_f32_e32 v0, v138, v0
	s_waitcnt lgkmcnt(0)
	v_mfma_f32_32x32x16_bf16 v[96:111], v[244:247], v[172:175], v[96:111]
	v_add_f32_e32 v0, v139, v0
	v_add_f32_e32 v0, v140, v0
	v_add_f32_e32 v0, v141, v0
	v_add_f32_e32 v0, v142, v0
	v_add_f32_e32 v0, v143, v0
	s_or_b64 exec, exec, s[20:21]
	s_and_saveexec_b64 s[20:21], s[4:5]
	ds_read_b64 v[6:7], v226 offset:32768
	ds_read_b64 v[8:9], v227 offset:32768
	ds_read_b64 v[10:11], v228 offset:45056
	ds_read_b64 v[12:13], v229 offset:45056
	ds_read_b64 v[242:243], v228 offset:36864
	ds_read_b64 v[244:245], v229 offset:36864
	ds_read_b64 v[128:129], v228 offset:40960
	ds_read_b64 v[130:131], v229 offset:40960
	ds_read_b64 v[132:133], v230 offset:32768
	ds_read_b64 v[134:135], v231 offset:32768
	s_waitcnt lgkmcnt(8)
	v_mfma_f32_32x32x16_bf16 v[64:79], v[6:9], v[208:211], v[64:79]
	ds_read_b64 v[6:7], v232 offset:45056
	ds_read_b64 v[8:9], v233 offset:45056
	s_waitcnt lgkmcnt(8)
	v_mfma_f32_32x32x16_bf16 v[112:127], v[10:13], v[208:211], v[112:127]
	ds_read_b64 v[10:11], v232 offset:36864
	ds_read_b64 v[12:13], v233 offset:36864
	s_waitcnt lgkmcnt(8)
	v_mfma_f32_32x32x16_bf16 v[48:63], v[242:245], v[208:211], v[48:63]
	ds_read_b64 v[242:243], v232 offset:40960
	ds_read_b64 v[244:245], v233 offset:40960
	s_waitcnt lgkmcnt(8)
	v_mfma_f32_32x32x16_bf16 v[32:47], v[128:131], v[208:211], v[32:47]
	ds_read_b64 v[128:129], v234 offset:32768
	ds_read_b64 v[130:131], v235 offset:32768
	v_cvt_pk_bf16_f32 v2, v136, v137
	v_cvt_pk_bf16_f32 v3, v138, v139
	v_cvt_pk_bf16_f32 v4, v140, v141
	v_cvt_pk_bf16_f32 v5, v142, v143
	s_nop 1
	ds_read_b64 v[136:137], v236 offset:45056
	ds_read_b64 v[138:139], v237 offset:45056
	s_waitcnt lgkmcnt(10)
	v_mfma_f32_32x32x16_bf16 v[64:79], v[132:135], v[2:5], v[64:79]
	ds_read_b64 v[140:141], v236 offset:36864
	ds_read_b64 v[142:143], v237 offset:36864
	v_exp_f32_e32 v144, v144
	v_exp_f32_e32 v145, v145
	s_waitcnt lgkmcnt(10)
	v_mfma_f32_32x32x16_bf16 v[112:127], v[6:9], v[2:5], v[112:127]
	ds_read_b64 v[132:133], v236 offset:40960
	ds_read_b64 v[134:135], v237 offset:40960
	v_exp_f32_e32 v146, v146
	v_exp_f32_e32 v147, v147
	v_add_f32_e32 v0, v144, v0
	v_add_f32_e32 v0, v145, v0
	s_waitcnt lgkmcnt(10)
	v_mfma_f32_32x32x16_bf16 v[48:63], v[10:13], v[2:5], v[48:63]
	ds_read_b64 v[6:7], v238 offset:32768
	ds_read_b64 v[8:9], v239 offset:32768
	v_exp_f32_e32 v148, v148
	v_exp_f32_e32 v149, v149
	v_add_f32_e32 v0, v146, v0
	v_add_f32_e32 v0, v147, v0
	s_waitcnt lgkmcnt(10)
	v_mfma_f32_32x32x16_bf16 v[32:47], v[242:245], v[2:5], v[32:47]
	ds_read_b64 v[10:11], v240 offset:36864
	ds_read_b64 v[12:13], v241 offset:36864
	v_exp_f32_e32 v150, v150
	v_exp_f32_e32 v151, v151
	v_add_f32_e32 v0, v148, v0
	v_add_f32_e32 v0, v149, v0
	v_add_f32_e32 v0, v150, v0
	v_add_f32_e32 v0, v151, v0
	v_cvt_pk_bf16_f32 v2, v144, v145
	v_cvt_pk_bf16_f32 v3, v146, v147
	v_cvt_pk_bf16_f32 v4, v148, v149
	v_cvt_pk_bf16_f32 v5, v150, v151
	s_nop 1
	ds_read_b64 v[242:243], v240 offset:40960
	ds_read_b64 v[244:245], v241 offset:40960
	s_waitcnt lgkmcnt(12)
	v_mfma_f32_32x32x16_bf16 v[64:79], v[128:131], v[2:5], v[64:79]
	ds_read_b64 v[144:145], v240 offset:45056
	ds_read_b64 v[146:147], v241 offset:45056
	v_exp_f32_e32 v152, v152
	v_exp_f32_e32 v153, v153
	s_waitcnt lgkmcnt(12)
	v_mfma_f32_32x32x16_bf16 v[112:127], v[136:139], v[2:5], v[112:127]
	v_exp_f32_e32 v154, v154
	v_exp_f32_e32 v155, v155
	v_add_f32_e32 v0, v152, v0
	v_add_f32_e32 v0, v153, v0
	s_waitcnt lgkmcnt(10)
	v_mfma_f32_32x32x16_bf16 v[48:63], v[140:143], v[2:5], v[48:63]
	v_exp_f32_e32 v156, v156
	v_exp_f32_e32 v157, v157
	v_add_f32_e32 v0, v154, v0
	v_add_f32_e32 v0, v155, v0
	s_waitcnt lgkmcnt(8)
	v_mfma_f32_32x32x16_bf16 v[32:47], v[132:135], v[2:5], v[32:47]
	v_exp_f32_e32 v158, v158
	v_exp_f32_e32 v159, v159
	v_add_f32_e32 v0, v156, v0
	v_add_f32_e32 v0, v157, v0
	v_add_f32_e32 v0, v158, v0
	v_add_f32_e32 v0, v159, v0
	v_cvt_pk_bf16_f32 v2, v152, v153
	v_cvt_pk_bf16_f32 v3, v154, v155
	v_cvt_pk_bf16_f32 v4, v156, v157
	v_cvt_pk_bf16_f32 v5, v158, v159
	s_nop 1
	s_waitcnt lgkmcnt(6)
	v_mfma_f32_32x32x16_bf16 v[64:79], v[6:9], v[2:5], v[64:79]
	s_waitcnt lgkmcnt(4)
	v_mfma_f32_32x32x16_bf16 v[48:63], v[10:13], v[2:5], v[48:63]
	s_waitcnt lgkmcnt(2)
	v_mfma_f32_32x32x16_bf16 v[32:47], v[242:245], v[2:5], v[32:47]
	s_waitcnt lgkmcnt(0)
	v_mfma_f32_32x32x16_bf16 v[112:127], v[144:147], v[2:5], v[112:127]
	v_add_f32_e32 v224, v0, v224
	s_branch .LBB0_1428
